# scan chunk loops: back-edge path waits vmcnt(13..4) instead of (9..0) at the loop top (the chunk's 4 output stores are younger than the tile loads and may stay in flight); prologue entry keeps the str
# baseline (speedup 1.0000x reference)
.LBB0_602:
	v_mov_b32_e32 v138, v110
	v_mov_b32_e32 v0, v108
	v_mov_b32_e32 v133, v111
	s_nop 0
	v_lshlrev_b32_e32 v68, 4, v0
	v_and_b32_e32 v64, 0xf0, v68
	v_add_u32_e32 v64, 0, v64
	v_lshrrev_b32_e32 v65, 4, v0
	v_add_u32_e32 v69, 0x200, v0
	v_mad_u64_u32 v[66:67], s[82:83], v65, s88, v[64:65]
	v_lshrrev_b32_e32 v65, 4, v69
	s_waitcnt vmcnt(13)
	ds_write_b128 v66, v[8:11]
	s_waitcnt vmcnt(12)
	ds_write_b128 v66, v[12:15] offset:36864
	v_mad_u64_u32 v[66:67], s[82:83], v65, s88, v[64:65]
	v_add_u32_e32 v65, 0x400, v0
	v_lshrrev_b32_e32 v65, 4, v65
	s_waitcnt vmcnt(11)
	ds_write_b128 v66, v[16:19]
	s_waitcnt vmcnt(10)
	ds_write_b128 v66, v[20:23] offset:36864
	v_mad_u64_u32 v[66:67], s[82:83], v65, s88, v[64:65]
	v_add_u32_e32 v65, 0x600, v0
	v_lshrrev_b32_e32 v65, 4, v65
	v_mad_u64_u32 v[64:65], s[82:83], v65, s88, v[64:65]
	s_waitcnt vmcnt(9)
	ds_write_b128 v66, v[24:27]
	s_waitcnt vmcnt(8)
	ds_write_b128 v66, v[28:31] offset:36864
	s_waitcnt vmcnt(7)
	ds_write_b128 v64, v[32:35]
	s_waitcnt vmcnt(6)
	ds_write_b128 v64, v[36:39] offset:36864
	v_and_b32_e32 v64, 0x70, v68
	v_add_u32_e32 v64, s90, v64
	v_lshrrev_b32_e32 v65, 3, v0
	v_mad_u64_u32 v[66:67], s[82:83], v65, s89, v[64:65]
	v_lshrrev_b32_e32 v65, 3, v69
	v_mad_u64_u32 v[64:65], s[82:83], v65, s89, v[64:65]
	v_cmp_gt_i32_e32 vcc, s85, v0
	s_waitcnt vmcnt(5)
	ds_write_b128 v66, v[40:43]
	s_waitcnt vmcnt(4)
	ds_write_b128 v64, v[44:47]
.Lst_a_join:
	s_and_saveexec_b64 s[82:83], vcc
	s_cbranch_execz .LBB0_605
	v_lshl_add_u32 v64, v0, 2, 0
	v_add_u32_e32 v65, 0x25a00, v64
	ds_write_b32 v65, v127
	v_xor_b32_e32 v65, 0x80000000, v127
	v_add_u32_e32 v66, 0x25c00, v64
	ds_write_b32 v66, v65
	v_add_u32_e32 v65, 0x25e00, v64
	ds_write_b32 v65, v134
	v_mul_f32_e32 v65, 0x3fb8aa3b, v127
	v_exp_f32_e32 v65, v65
	v_add_u32_e32 v66, 0x26000, v64
	v_add_u32_e32 v64, 0x26200, v64
	v_cmp_eq_u32_e32 vcc, 0, v0
	ds_write_b32 v66, v65
	v_sub_f32_e32 v65, v135, v127
	v_mul_f32_e32 v65, 0x3fb8aa3b, v65
	v_exp_f32_e32 v65, v65
	s_nop 0
	v_mul_f32_e32 v65, v134, v65
	ds_write_b32 v64, v65
	s_and_b64 exec, exec, vcc
	s_cbranch_execz .LBB0_605
	v_mul_f32_e32 v0, 0x3fb8aa3b, v135
	v_exp_f32_e32 v0, v0
	v_mov_b32_e32 v64, s10
	ds_write_b64 v64, v[0:1]

.Lrx_b_join:
	s_and_saveexec_b64 s[78:79], vcc
	s_cbranch_execz .LBB0_625
	v_max_f32_e32 v69, v175, v175
	v_max_f32_e32 v70, v129, v129
	v_max_f32_e32 v69, v70, v69
	v_max_f32_e64 v70, -v174, -v174
	v_max_f32_e64 v71, -v129, -v129
	v_min_f32_e32 v70, v71, v70
	v_lshl_add_u32 v71, v68, 2, 0
	v_add_u32_e32 v72, 0x25a00, v71
	ds_write_b32 v72, v70
	v_add_u32_e32 v72, 0x25c00, v71
	ds_write_b32 v72, v127
	v_add_u32_e32 v72, 0x25e00, v71
	ds_write_b32 v72, v170
	v_add_f32_e32 v72, v129, v70
	v_mul_f32_e32 v72, 0x3fb8aa3b, v72
	v_exp_f32_e32 v72, v72
	v_add_u32_e32 v73, 0x26000, v71
	v_sub_f32_e32 v70, v173, v70
	v_mul_f32_e32 v70, 0xbfb8aa3b, v70
	v_mul_f32_e32 v72, 0x3db504f3, v72
	ds_write_b32 v73, v72
	v_sub_f32_e32 v72, v127, v69
	v_mul_f32_e32 v72, 0x3fb8aa3b, v72
	v_exp_f32_e32 v72, v72
	v_exp_f32_e32 v70, v70
	v_add_u32_e32 v73, 0x26200, v71
	v_add_u32_e32 v71, 0x26400, v71
	v_cmp_eq_u32_e32 vcc, 0, v68
	ds_write_b32 v73, v72
	ds_write_b32 v71, v70
	s_and_b64 exec, exec, vcc
	s_cbranch_execz .LBB0_625
	v_sub_f32_e32 v68, v129, v69
	v_mul_f32_e32 v68, 0x3fb8aa3b, v68
	v_exp_f32_e32 v68, v68
	v_add_f32_e32 v69, v176, v69
	v_mov_b32_e32 v70, s10
	ds_write_b64 v70, v[68:69]

.Lst_a:
	v_mov_b32_e32 v138, v110
	v_mov_b32_e32 v0, v108
	v_mov_b32_e32 v133, v111
	s_nop 0
	v_lshlrev_b32_e32 v68, 4, v0
	v_and_b32_e32 v64, 0xf0, v68
	v_add_u32_e32 v64, 0, v64
	v_lshrrev_b32_e32 v65, 4, v0
	v_add_u32_e32 v69, 0x200, v0
	v_mad_u64_u32 v[66:67], s[82:83], v65, s88, v[64:65]
	v_lshrrev_b32_e32 v65, 4, v69
	s_waitcnt vmcnt(9)
	ds_write_b128 v66, v[8:11]
	s_waitcnt vmcnt(8)
	ds_write_b128 v66, v[12:15] offset:36864
	v_mad_u64_u32 v[66:67], s[82:83], v65, s88, v[64:65]
	v_add_u32_e32 v65, 0x400, v0
	v_lshrrev_b32_e32 v65, 4, v65
	s_waitcnt vmcnt(7)
	ds_write_b128 v66, v[16:19]
	s_waitcnt vmcnt(6)
	ds_write_b128 v66, v[20:23] offset:36864
	v_mad_u64_u32 v[66:67], s[82:83], v65, s88, v[64:65]
	v_add_u32_e32 v65, 0x600, v0
	v_lshrrev_b32_e32 v65, 4, v65
	v_mad_u64_u32 v[64:65], s[82:83], v65, s88, v[64:65]
	s_waitcnt vmcnt(5)
	ds_write_b128 v66, v[24:27]
	s_waitcnt vmcnt(4)
	ds_write_b128 v66, v[28:31] offset:36864
	s_waitcnt vmcnt(3)
	ds_write_b128 v64, v[32:35]
	s_waitcnt vmcnt(2)
	ds_write_b128 v64, v[36:39] offset:36864
	v_and_b32_e32 v64, 0x70, v68
	v_add_u32_e32 v64, s90, v64
	v_lshrrev_b32_e32 v65, 3, v0
	v_mad_u64_u32 v[66:67], s[82:83], v65, s89, v[64:65]
	v_lshrrev_b32_e32 v65, 3, v69
	v_mad_u64_u32 v[64:65], s[82:83], v65, s89, v[64:65]
	v_cmp_gt_i32_e32 vcc, s85, v0
	s_waitcnt vmcnt(1)
	ds_write_b128 v66, v[40:43]
	s_waitcnt vmcnt(0)
	ds_write_b128 v64, v[44:47]
	s_branch .Lst_a_join
.Lrx_b:
	v_mov_b32_e32 v141, v110
	v_mov_b32_e32 v68, v108
	v_mov_b32_e32 v142, v111
	s_nop 0
	v_lshlrev_b32_e32 v69, 4, v68
	v_and_b32_e32 v70, 0xf0, v69
	v_add_u32_e32 v70, 0, v70
	v_lshrrev_b32_e32 v71, 4, v68
	v_add_u32_e32 v74, 0x200, v68
	v_mad_u64_u32 v[72:73], s[78:79], v71, s88, v[70:71]
	v_lshrrev_b32_e32 v71, 4, v74
	s_waitcnt vmcnt(13)
	ds_write_b128 v72, v[8:11]
	s_waitcnt vmcnt(12)
	ds_write_b128 v72, v[12:15] offset:36864
	v_mad_u64_u32 v[72:73], s[78:79], v71, s88, v[70:71]
	v_add_u32_e32 v71, 0x400, v68
	v_lshrrev_b32_e32 v71, 4, v71
	s_waitcnt vmcnt(11)
	ds_write_b128 v72, v[16:19]
	s_waitcnt vmcnt(10)
	ds_write_b128 v72, v[20:23] offset:36864
	v_mad_u64_u32 v[72:73], s[78:79], v71, s88, v[70:71]
	v_add_u32_e32 v71, 0x600, v68
	v_lshrrev_b32_e32 v71, 4, v71
	v_mad_u64_u32 v[70:71], s[78:79], v71, s88, v[70:71]
	v_and_b32_e32 v69, 0x70, v69
	s_waitcnt vmcnt(9)
	ds_write_b128 v72, v[24:27]
	s_waitcnt vmcnt(8)
	ds_write_b128 v72, v[28:31] offset:36864
	s_waitcnt vmcnt(7)
	ds_write_b128 v70, v[32:35]
	s_waitcnt vmcnt(6)
	ds_write_b128 v70, v[36:39] offset:36864
	v_add_u32_e32 v70, s90, v69
	v_lshrrev_b32_e32 v69, 3, v68
	v_mad_u64_u32 v[72:73], s[78:79], v69, s89, v[70:71]
	v_lshrrev_b32_e32 v69, 3, v74
	v_mad_u64_u32 v[70:71], s[78:79], v69, s89, v[70:71]
	v_cmp_gt_i32_e32 vcc, s85, v68
	s_waitcnt vmcnt(5)
	ds_write_b128 v72, v[40:43]
	s_waitcnt vmcnt(4)
	ds_write_b128 v70, v[44:47]
	s_branch .Lrx_b_join
